# baseline (speedup 1.0000x reference)
; #define PG8_STAGE(bufoff, gbase, voff) do { _Pragma("unroll") for (int _i = 0; _i < 2; ++_i) \
;         __builtin_amdgcn_global_load_lds((const unsigned*)((const char*)(gbase) + (voff)[_i]), (LAS unsigned*)(lds + (bufoff) + ldsw + _i * 8192), 16, 0, 0); } while (0)
; #define PG8_LDA(dst, b, h) do { _Pragma("unroll") for (int m = 0; m < 4; ++m) _Pragma("unroll") for (int k = 0; k < 2; ++k) dst[m][k] = *(const LAS bf16x8*)(lds + PG8_SA(b, h) + aoff + m * 2048 + k * 1024); } while (0)
; #define PG8_WAIT_V(n) asm volatile("s_waitcnt vmcnt(" #n ")" ::: "memory")
; template <class Epi>
; __device__ __forceinline__ void gemm_phase(const int tid, LAS unsigned char* lds, const Gemm g, const StaticOrder& S, const Epi& E) {
;     ...
;     for (;;) {
;         const bool has_next = S.next(ui + 1, nxt);
;         const char* nA = has_next ? (const char*)g.A + (size_t)nxt.pm * tstep : cA; const char* nB = has_next ? (const char*)g.Bt + (size_t)nxt.pn * tstep : cB;
;         for (int t = 0; t < nt; t += 2) {
;             const bool last = (t == nt - 2);
;             const char* a2 = last ? nA : cA + (size_t)(t + 2) * kstep; const char* b2 = last ? nB : cB + (size_t)(t + 2) * kstep;
;             const char* a3 = a2 + kstep; const char* b3 = b2 + kstep;
;             PG8_LDB(B0, 0, 0); PG8_SCHED; PG8_LDA(At, 0, 0);
;             PG8_WAIT_L(8); PG8_BAR; PG8_WAIT_L(0); PG8_MMA(0, 0, At, B0); PG8_BAR; PG8_SCHED;
;             PG8_LDB(B1, 0, 1); PG8_STAGE(PG8_SB(0, 0), b2, voffB);
;             PG8_BAR; PG8_WAIT_L(0); PG8_MMA(0, 1, At, B1); PG8_BAR;
;             PG8_LDA(At, 0, 1); PG8_STAGE(PG8_SA(0, 0), a2, voffA);
;             PG8_BAR; PG8_WAIT_L(0); PG8_MMA(1, 0, At, B0); PG8_BAR; PG8_SCHED;
;             PG8_STAGE(PG8_SB(0, 1), b2 + hstep, voffB);
;             { const int first_ = __builtin_amdgcn_readfirstlane((ui > 0 && t == 0) ? 1 : 0);
;               if constexpr (Epi::SMIN == 8) asm volatile("s_cmp_eq_u32 %0, 0\n\ts_cbranch_scc1 .Lws_a%=\n\ts_waitcnt vmcnt(14)\n\ts_branch .Lws_b%=\n.Lws_a%=:\n\ts_waitcnt vmcnt(6)\n.Lws_b%=:" :: "s"(first_) : "memory", "scc");
;               else if constexpr (Epi::SMIN == 24) asm volatile("s_cmp_eq_u32 %0, 0\n\ts_cbranch_scc1 .Lws_a%=\n\ts_waitcnt vmcnt(30)\n\ts_branch .Lws_b%=\n.Lws_a%=:\n\ts_waitcnt vmcnt(6)\n.Lws_b%=:" :: "s"(first_) : "memory", "scc");
;               else PG8_WAIT_V(6); }
.LBB0_447:
	v_mov_b64_e32 v[2:3], 0x1020
	s_ashr_i32 s13, s12, 31
	v_cmp_lt_i64_e32 vcc, s[14:15], v[2:3]
	s_lshl_b64 s[14:15], s[12:13], 20
	s_add_u32 s14, s62, s14
	s_addc_u32 s15, s63, s15
	s_and_b64 s[16:17], vcc, exec
	s_cselect_b32 s13, s15, s37
	s_cselect_b32 s57, s14, s36
	s_ashr_i32 s11, s10, 31
	s_lshl_b64 s[16:17], s[10:11], 20
	s_add_u32 s16, s26, s16
	s_addc_u32 s17, s27, s17
	s_and_b64 s[58:59], vcc, exec
	s_cselect_b32 s11, s17, s25
	s_cselect_b32 s58, s16, s24
	s_cmp_lg_u32 s22, 0
	s_cselect_b64 s[22:23], -1, 0
	s_add_u32 s59, s36, 0x100
	s_addc_u32 s60, s37, 0
	s_add_u32 s61, s24, 0x100
	s_addc_u32 s64, s25, 0
	s_mov_b32 s65, -2
	v_add_u32_e32 v250, 0x10000, v155
	v_add_u32_e32 v251, 0x14000, v155
	v_add_u32_e32 v252, 0x18000, v155
	v_add_u32_e32 v253, 0x1c000, v155
	s_add_i32 s66, 0, 0x10000
	ds_read_b128 v[130:133], v250
	ds_read_b128 v[142:145], v250 offset:1024
	ds_read_b128 v[146:149], v250 offset:2048
	ds_read_b128 v[150:153], v250 offset:3072
	s_cmp_eq_u32 s65, 28
	s_cselect_b32 s25, s13, s60
	s_cselect_b32 s24, s57, s59
	s_cselect_b32 s37, s11, s64
	s_cselect_b32 s36, s58, s61
	ds_read_b128 v[160:163], v158
	ds_read_b128 v[164:167], v158 offset:1024
	ds_read_b128 v[168:171], v158 offset:2048
	ds_read_b128 v[172:175], v158 offset:3072
	ds_read_b128 v[176:179], v158 offset:4096
	ds_read_b128 v[180:183], v158 offset:5120
	ds_read_b128 v[184:187], v158 offset:6144
	ds_read_b128 v[188:191], v158 offset:7168
	s_waitcnt lgkmcnt(8)
	s_barrier
	s_setprio 1
	s_waitcnt lgkmcnt(7)
	v_mfma_f32_16x16x32_bf16 v[126:129], v[130:133], v[160:163], 0
	v_mfma_f32_16x16x32_bf16 v[118:121], v[146:149], v[160:163], 0
	s_waitcnt lgkmcnt(5)
	v_mfma_f32_16x16x32_bf16 v[110:113], v[130:133], v[168:171], 0
	v_mfma_f32_16x16x32_bf16 v[102:105], v[146:149], v[168:171], 0
	s_waitcnt lgkmcnt(3)
	v_mfma_f32_16x16x32_bf16 v[94:97], v[130:133], v[176:179], 0
	v_mfma_f32_16x16x32_bf16 v[86:89], v[146:149], v[176:179], 0
	s_waitcnt lgkmcnt(1)
	v_mfma_f32_16x16x32_bf16 v[78:81], v[130:133], v[184:187], 0
	v_mfma_f32_16x16x32_bf16 v[70:73], v[146:149], v[184:187], 0
	v_mfma_f32_16x16x32_bf16 v[126:129], v[142:145], v[164:167], v[126:129]
	v_mfma_f32_16x16x32_bf16 v[118:121], v[150:153], v[164:167], v[118:121]
	v_mfma_f32_16x16x32_bf16 v[110:113], v[142:145], v[172:175], v[110:113]
	v_mfma_f32_16x16x32_bf16 v[102:105], v[150:153], v[172:175], v[102:105]
	v_mfma_f32_16x16x32_bf16 v[94:97], v[142:145], v[180:183], v[94:97]
	v_mfma_f32_16x16x32_bf16 v[86:89], v[150:153], v[180:183], v[86:89]
	s_waitcnt lgkmcnt(0)
	v_mfma_f32_16x16x32_bf16 v[78:81], v[142:145], v[188:191], v[78:81]
	v_mfma_f32_16x16x32_bf16 v[70:73], v[150:153], v[188:191], v[70:73]
	s_setprio 0
	s_barrier
	s_add_i32 s68, 0, 0x14000
	s_add_i32 s66, s66, s28
	s_mov_b32 m0, s66
	ds_read_b128 v[192:195], v251
	ds_read_b128 v[196:199], v251 offset:1024
	ds_read_b128 v[200:203], v251 offset:2048
	ds_read_b128 v[204:207], v251 offset:3072
	global_load_lds_dwordx4 v0, s[36:37]
	s_add_i32 m0, s66, 0x2000
	s_nop 0
	global_load_lds_dwordx4 v134, s[36:37]
	s_barrier
	s_setprio 1
	s_waitcnt lgkmcnt(3)
	v_mfma_f32_16x16x32_bf16 v[122:125], v[192:195], v[160:163], 0
	s_waitcnt lgkmcnt(1)
	v_mfma_f32_16x16x32_bf16 v[114:117], v[200:203], v[160:163], 0
	v_mfma_f32_16x16x32_bf16 v[106:109], v[192:195], v[168:171], 0
	v_mfma_f32_16x16x32_bf16 v[98:101], v[200:203], v[168:171], 0
	v_mfma_f32_16x16x32_bf16 v[90:93], v[192:195], v[176:179], 0
	v_mfma_f32_16x16x32_bf16 v[82:85], v[200:203], v[176:179], 0
	v_mfma_f32_16x16x32_bf16 v[74:77], v[192:195], v[184:187], 0
	v_mfma_f32_16x16x32_bf16 v[66:69], v[200:203], v[184:187], 0
	v_mfma_f32_16x16x32_bf16 v[122:125], v[196:199], v[164:167], v[122:125]
	s_waitcnt lgkmcnt(0)
	v_mfma_f32_16x16x32_bf16 v[114:117], v[204:207], v[164:167], v[114:117]
	v_mfma_f32_16x16x32_bf16 v[106:109], v[196:199], v[172:175], v[106:109]
	v_mfma_f32_16x16x32_bf16 v[98:101], v[204:207], v[172:175], v[98:101]
	v_mfma_f32_16x16x32_bf16 v[90:93], v[196:199], v[180:183], v[90:93]
	v_mfma_f32_16x16x32_bf16 v[82:85], v[204:207], v[180:183], v[82:85]
	v_mfma_f32_16x16x32_bf16 v[74:77], v[196:199], v[188:191], v[74:77]
	v_mfma_f32_16x16x32_bf16 v[66:69], v[204:207], v[188:191], v[66:69]
	s_setprio 0
	s_mov_b32 m0, s30
	s_barrier
	ds_read_b128 v[160:163], v158 offset:16384
	ds_read_b128 v[164:167], v158 offset:17408
	ds_read_b128 v[168:171], v158 offset:18432
	ds_read_b128 v[172:175], v158 offset:19456
	ds_read_b128 v[176:179], v158 offset:20480
	ds_read_b128 v[180:183], v158 offset:21504
	ds_read_b128 v[184:187], v158 offset:22528
	ds_read_b128 v[188:191], v158 offset:23552
	global_load_lds_dwordx4 v138, s[24:25]
	s_mov_b32 m0, s38
	s_nop 0
	global_load_lds_dwordx4 v136, s[24:25]
	s_barrier
	s_setprio 1
	s_waitcnt lgkmcnt(7)
	v_mfma_f32_16x16x32_bf16 v[62:65], v[130:133], v[160:163], 0
	v_mfma_f32_16x16x32_bf16 v[54:57], v[146:149], v[160:163], 0
	s_waitcnt lgkmcnt(5)
	v_mfma_f32_16x16x32_bf16 v[46:49], v[130:133], v[168:171], 0
	v_mfma_f32_16x16x32_bf16 v[38:41], v[146:149], v[168:171], 0
	s_waitcnt lgkmcnt(3)
	v_mfma_f32_16x16x32_bf16 v[30:33], v[130:133], v[176:179], 0
	v_mfma_f32_16x16x32_bf16 v[22:25], v[146:149], v[176:179], 0
	s_waitcnt lgkmcnt(1)
	v_mfma_f32_16x16x32_bf16 v[14:17], v[130:133], v[184:187], 0
	v_mfma_f32_16x16x32_bf16 v[6:9], v[146:149], v[184:187], 0
	v_mfma_f32_16x16x32_bf16 v[62:65], v[142:145], v[164:167], v[62:65]
	v_mfma_f32_16x16x32_bf16 v[54:57], v[150:153], v[164:167], v[54:57]
	v_mfma_f32_16x16x32_bf16 v[46:49], v[142:145], v[172:175], v[46:49]
	v_mfma_f32_16x16x32_bf16 v[38:41], v[150:153], v[172:175], v[38:41]
	v_mfma_f32_16x16x32_bf16 v[30:33], v[142:145], v[180:183], v[30:33]
	v_mfma_f32_16x16x32_bf16 v[22:25], v[150:153], v[180:183], v[22:25]
	s_waitcnt lgkmcnt(0)
	v_mfma_f32_16x16x32_bf16 v[14:17], v[142:145], v[188:191], v[14:17]
	v_mfma_f32_16x16x32_bf16 v[6:9], v[150:153], v[188:191], v[6:9]
	s_setprio 0
	s_barrier
	s_add_u32 s66, s36, 0x80000
	s_addc_u32 s67, s37, 0
	s_add_i32 s68, s68, s28
	s_mov_b32 m0, s68
	s_nop 0
	global_load_lds_dwordx4 v0, s[66:67]
	s_add_i32 m0, s68, 0x2000
	s_cmp_eq_u32 s65, -2
	global_load_lds_dwordx4 v134, s[66:67]
	s_cselect_b64 s[66:67], -1, 0
	s_and_b64 s[66:67], s[22:23], s[66:67]
	v_cndmask_b32_e64 v130, 0, 1, s[66:67]
	s_nop 0
	v_readfirstlane_b32 s66, v130
	s_and_b32 s66, s66, 1
	s_cmp_eq_u32 s66, 0
	s_cbranch_scc1 .Lws_a1_pl
	s_waitcnt vmcnt(14)
	s_branch .Lws_b1_pl

; #define PG8_STAGE(bufoff, gbase, voff) do { _Pragma("unroll") for (int _i = 0; _i < 2; ++_i) \
;         __builtin_amdgcn_global_load_lds((const unsigned*)((const char*)(gbase) + (voff)[_i]), (LAS unsigned*)(lds + (bufoff) + ldsw + _i * 8192), 16, 0, 0); } while (0)
; #define PG8_LDA(dst, b, h) do { _Pragma("unroll") for (int m = 0; m < 4; ++m) _Pragma("unroll") for (int k = 0; k < 2; ++k) dst[m][k] = *(const LAS bf16x8*)(lds + PG8_SA(b, h) + aoff + m * 2048 + k * 1024); } while (0)
; #define PG8_LDB(dst, b, h) do { _Pragma("unroll") for (int n = 0; n < 2; ++n) _Pragma("unroll") for (int k = 0; k < 2; ++k) dst[n][k] = *(const LAS bf16x8*)(lds + PG8_SB(b, h) + boff + n * 2048 + k * 1024); } while (0)
; #define PG8_MMA(ai, bj, At, Bt) do { __builtin_amdgcn_s_setprio(1); _Pragma("unroll") for (int m = 0; m < 4; ++m) _Pragma("unroll") for (int n = 0; n < 2; ++n) _Pragma("unroll") for (int k = 0; k < 2; ++k) \
;         acc[ai][bj][m][n] = __builtin_amdgcn_mfma_f32_16x16x32_bf16(Bt[n][k], At[m][k], acc[ai][bj][m][n], 0, 0, 0); __builtin_amdgcn_s_setprio(0); } while (0)
; #define PG8_WAIT_L(n) asm volatile("s_waitcnt lgkmcnt(" #n ")" ::: "memory")
; #define PG8_BAR __builtin_amdgcn_s_barrier()
; #define PG8_SCHED __builtin_amdgcn_sched_barrier(0)
; template <class Epi>
; __device__ __forceinline__ void gemm_phase(const int tid, LAS unsigned char* lds, const Gemm g, const StaticOrder& S, const Epi& E) {
;     ...
;             PG8_BAR; PG8_MMA(1, 1, At, B1); PG8_BAR;
;             PG8_LDB(B0, 1, 0); PG8_SCHED; PG8_LDA(At, 1, 0); PG8_STAGE(PG8_SA(0, 1), a2 + hstep, voffA);
;             PG8_WAIT_L(8); PG8_BAR; PG8_WAIT_L(0); PG8_MMA(0, 0, At, B0); PG8_BAR; PG8_SCHED;
;             PG8_LDB(B1, 1, 1); PG8_STAGE(PG8_SB(1, 0), b3, voffB);
;             PG8_BAR; PG8_WAIT_L(0); PG8_MMA(0, 1, At, B1); PG8_BAR;
;             PG8_LDA(At, 1, 1); PG8_STAGE(PG8_SA(1, 0), a3, voffA);
;             PG8_BAR; PG8_WAIT_L(0); PG8_MMA(1, 0, At, B0); PG8_BAR; PG8_SCHED;
.Lws_b1_pl:
	s_barrier
	s_setprio 1
	v_mfma_f32_16x16x32_bf16 v[58:61], v[192:195], v[160:163], 0
	v_mfma_f32_16x16x32_bf16 v[50:53], v[200:203], v[160:163], 0
	v_mfma_f32_16x16x32_bf16 v[42:45], v[192:195], v[168:171], 0
	v_mfma_f32_16x16x32_bf16 v[34:37], v[200:203], v[168:171], 0
	v_mfma_f32_16x16x32_bf16 v[26:29], v[192:195], v[176:179], 0
	v_mfma_f32_16x16x32_bf16 v[18:21], v[200:203], v[176:179], 0
	v_mfma_f32_16x16x32_bf16 v[10:13], v[192:195], v[184:187], 0
	v_mfma_f32_16x16x32_bf16 v[2:5], v[200:203], v[184:187], 0
	v_mfma_f32_16x16x32_bf16 v[58:61], v[196:199], v[164:167], v[58:61]
	v_mfma_f32_16x16x32_bf16 v[50:53], v[204:207], v[164:167], v[50:53]
	v_mfma_f32_16x16x32_bf16 v[42:45], v[196:199], v[172:175], v[42:45]
	v_mfma_f32_16x16x32_bf16 v[34:37], v[204:207], v[172:175], v[34:37]
	v_mfma_f32_16x16x32_bf16 v[26:29], v[196:199], v[180:183], v[26:29]
	v_mfma_f32_16x16x32_bf16 v[18:21], v[204:207], v[180:183], v[18:21]
	v_mfma_f32_16x16x32_bf16 v[10:13], v[196:199], v[188:191], v[10:13]
	v_mfma_f32_16x16x32_bf16 v[2:5], v[204:207], v[188:191], v[2:5]
	s_setprio 0
	s_add_i32 s68, 0, 0x18000
	s_barrier
	ds_read_b128 v[130:133], v252
	ds_read_b128 v[142:145], v252 offset:1024
	ds_read_b128 v[146:149], v252 offset:2048
	ds_read_b128 v[150:153], v252 offset:3072
	s_add_u32 s66, s24, 0x80000
	s_addc_u32 s67, s25, 0
	s_mov_b32 m0, s39
	ds_read_b128 v[160:163], v158 offset:32768
	ds_read_b128 v[164:167], v158 offset:33792
	ds_read_b128 v[168:171], v158 offset:34816
	ds_read_b128 v[172:175], v158 offset:35840
	ds_read_b128 v[176:179], v158 offset:36864
	ds_read_b128 v[180:183], v158 offset:37888
	ds_read_b128 v[184:187], v158 offset:38912
	ds_read_b128 v[188:191], v158 offset:39936
	global_load_lds_dwordx4 v138, s[66:67]
	s_mov_b32 m0, s46
	s_nop 0
	global_load_lds_dwordx4 v136, s[66:67]
	s_waitcnt lgkmcnt(8)
	s_barrier
	s_setprio 1
	s_waitcnt lgkmcnt(7)
	v_mfma_f32_16x16x32_bf16 v[126:129], v[130:133], v[160:163], v[126:129]
	v_mfma_f32_16x16x32_bf16 v[118:121], v[146:149], v[160:163], v[118:121]
	s_waitcnt lgkmcnt(5)
	v_mfma_f32_16x16x32_bf16 v[110:113], v[130:133], v[168:171], v[110:113]
	v_mfma_f32_16x16x32_bf16 v[102:105], v[146:149], v[168:171], v[102:105]
	s_waitcnt lgkmcnt(3)
	v_mfma_f32_16x16x32_bf16 v[94:97], v[130:133], v[176:179], v[94:97]
	v_mfma_f32_16x16x32_bf16 v[86:89], v[146:149], v[176:179], v[86:89]
	s_waitcnt lgkmcnt(1)
	v_mfma_f32_16x16x32_bf16 v[78:81], v[130:133], v[184:187], v[78:81]
	v_mfma_f32_16x16x32_bf16 v[70:73], v[146:149], v[184:187], v[70:73]
	v_mfma_f32_16x16x32_bf16 v[126:129], v[142:145], v[164:167], v[126:129]
	v_mfma_f32_16x16x32_bf16 v[118:121], v[150:153], v[164:167], v[118:121]
	v_mfma_f32_16x16x32_bf16 v[110:113], v[142:145], v[172:175], v[110:113]
	v_mfma_f32_16x16x32_bf16 v[102:105], v[150:153], v[172:175], v[102:105]
	v_mfma_f32_16x16x32_bf16 v[94:97], v[142:145], v[180:183], v[94:97]
	v_mfma_f32_16x16x32_bf16 v[86:89], v[150:153], v[180:183], v[86:89]
	s_waitcnt lgkmcnt(0)
	v_mfma_f32_16x16x32_bf16 v[78:81], v[142:145], v[188:191], v[78:81]
	v_mfma_f32_16x16x32_bf16 v[70:73], v[150:153], v[188:191], v[70:73]
	s_setprio 0
	s_barrier
	s_add_i32 s66, 0, 0x1c000
	s_add_i32 s67, s68, s28
	s_add_i32 m0, s67, 0xffffff80
	ds_read_b128 v[192:195], v253
	ds_read_b128 v[196:199], v253 offset:1024
	ds_read_b128 v[200:203], v253 offset:2048
	ds_read_b128 v[204:207], v253 offset:3072
	global_load_lds_dwordx4 v0, s[36:37] offset:128
	s_add_i32 m0, s67, 0x1f80
	s_nop 0
	global_load_lds_dwordx4 v134, s[36:37] offset:128
	s_barrier
; #define PG8_STAGE(bufoff, gbase, voff) do { _Pragma("unroll") for (int _i = 0; _i < 2; ++_i) \
;         __builtin_amdgcn_global_load_lds((const unsigned*)((const char*)(gbase) + (voff)[_i]), (LAS unsigned*)(lds + (bufoff) + ldsw + _i * 8192), 16, 0, 0); } while (0)
; #define PG8_LDA(dst, b, h) do { _Pragma("unroll") for (int m = 0; m < 4; ++m) _Pragma("unroll") for (int k = 0; k < 2; ++k) dst[m][k] = *(const LAS bf16x8*)(lds + PG8_SA(b, h) + aoff + m * 2048 + k * 1024); } while (0)
; #define PG8_MMA(ai, bj, At, Bt) do { __builtin_amdgcn_s_setprio(1); _Pragma("unroll") for (int m = 0; m < 4; ++m) _Pragma("unroll") for (int n = 0; n < 2; ++n) _Pragma("unroll") for (int k = 0; k < 2; ++k) \
;         acc[ai][bj][m][n] = __builtin_amdgcn_mfma_f32_16x16x32_bf16(Bt[n][k], At[m][k], acc[ai][bj][m][n], 0, 0, 0); __builtin_amdgcn_s_setprio(0); } while (0)
; #define PG8_WAIT_V(n) asm volatile("s_waitcnt vmcnt(" #n ")" ::: "memory")
; #define PG8_WAIT_L(n) asm volatile("s_waitcnt lgkmcnt(" #n ")" ::: "memory")
; #define PG8_BAR __builtin_amdgcn_s_barrier()
; #define PG8_SCHED __builtin_amdgcn_sched_barrier(0)
; template <class Epi>
; __device__ __forceinline__ void gemm_phase(const int tid, LAS unsigned char* lds, const Gemm g, const StaticOrder& S, const Epi& E) {
;     ...
;             PG8_BAR; PG8_WAIT_L(0); PG8_MMA(0, 1, At, B1); PG8_BAR;
;             PG8_LDA(At, 1, 1); PG8_STAGE(PG8_SA(1, 0), a3, voffA);
;             PG8_BAR; PG8_WAIT_L(0); PG8_MMA(1, 0, At, B0); PG8_BAR; PG8_SCHED;
;             PG8_STAGE(PG8_SB(1, 1), b3 + hstep, voffB);
;             PG8_WAIT_V(6); PG8_BAR; PG8_STAGE(PG8_SA(1, 1), a3 + hstep, voffA);
;             PG8_MMA(1, 1, At, B1); PG8_BAR;
	s_setprio 1
	s_waitcnt lgkmcnt(3)
	v_mfma_f32_16x16x32_bf16 v[122:125], v[192:195], v[160:163], v[122:125]
	s_waitcnt lgkmcnt(1)
	v_mfma_f32_16x16x32_bf16 v[114:117], v[200:203], v[160:163], v[114:117]
	v_mfma_f32_16x16x32_bf16 v[106:109], v[192:195], v[168:171], v[106:109]
	v_mfma_f32_16x16x32_bf16 v[98:101], v[200:203], v[168:171], v[98:101]
	v_mfma_f32_16x16x32_bf16 v[90:93], v[192:195], v[176:179], v[90:93]
	v_mfma_f32_16x16x32_bf16 v[82:85], v[200:203], v[176:179], v[82:85]
	v_mfma_f32_16x16x32_bf16 v[74:77], v[192:195], v[184:187], v[74:77]
	v_mfma_f32_16x16x32_bf16 v[66:69], v[200:203], v[184:187], v[66:69]
	v_mfma_f32_16x16x32_bf16 v[122:125], v[196:199], v[164:167], v[122:125]
	s_waitcnt lgkmcnt(0)
	v_mfma_f32_16x16x32_bf16 v[114:117], v[204:207], v[164:167], v[114:117]
	v_mfma_f32_16x16x32_bf16 v[106:109], v[196:199], v[172:175], v[106:109]
	v_mfma_f32_16x16x32_bf16 v[98:101], v[204:207], v[172:175], v[98:101]
	v_mfma_f32_16x16x32_bf16 v[90:93], v[196:199], v[180:183], v[90:93]
	v_mfma_f32_16x16x32_bf16 v[82:85], v[204:207], v[180:183], v[82:85]
	v_mfma_f32_16x16x32_bf16 v[74:77], v[196:199], v[188:191], v[74:77]
	v_mfma_f32_16x16x32_bf16 v[66:69], v[204:207], v[188:191], v[66:69]
	s_setprio 0
	s_add_i32 m0, s47, 0xffffff80
	s_barrier
	ds_read_b128 v[160:163], v158 offset:49152
	ds_read_b128 v[164:167], v158 offset:50176
	ds_read_b128 v[168:171], v158 offset:51200
	ds_read_b128 v[172:175], v158 offset:52224
	ds_read_b128 v[176:179], v158 offset:53248
	ds_read_b128 v[180:183], v158 offset:54272
	ds_read_b128 v[184:187], v158 offset:55296
	ds_read_b128 v[188:191], v158 offset:56320
	global_load_lds_dwordx4 v138, s[24:25] offset:128
	s_add_i32 m0, s48, 0xffffff80
	s_nop 0
	global_load_lds_dwordx4 v136, s[24:25] offset:128
	s_barrier
	s_setprio 1
	s_waitcnt lgkmcnt(7)
	v_mfma_f32_16x16x32_bf16 v[62:65], v[130:133], v[160:163], v[62:65]
	v_mfma_f32_16x16x32_bf16 v[54:57], v[146:149], v[160:163], v[54:57]
	s_waitcnt lgkmcnt(5)
	v_mfma_f32_16x16x32_bf16 v[46:49], v[130:133], v[168:171], v[46:49]
	v_mfma_f32_16x16x32_bf16 v[38:41], v[146:149], v[168:171], v[38:41]
	s_waitcnt lgkmcnt(3)
	v_mfma_f32_16x16x32_bf16 v[30:33], v[130:133], v[176:179], v[30:33]
	v_mfma_f32_16x16x32_bf16 v[22:25], v[146:149], v[176:179], v[22:25]
	s_waitcnt lgkmcnt(1)
	v_mfma_f32_16x16x32_bf16 v[14:17], v[130:133], v[184:187], v[14:17]
	v_mfma_f32_16x16x32_bf16 v[6:9], v[146:149], v[184:187], v[6:9]
	v_mfma_f32_16x16x32_bf16 v[62:65], v[142:145], v[164:167], v[62:65]
	v_mfma_f32_16x16x32_bf16 v[54:57], v[150:153], v[164:167], v[54:57]
	v_mfma_f32_16x16x32_bf16 v[46:49], v[142:145], v[172:175], v[46:49]
	v_mfma_f32_16x16x32_bf16 v[38:41], v[150:153], v[172:175], v[38:41]
	v_mfma_f32_16x16x32_bf16 v[30:33], v[142:145], v[180:183], v[30:33]
	v_mfma_f32_16x16x32_bf16 v[22:25], v[150:153], v[180:183], v[22:25]
	s_waitcnt lgkmcnt(0)
	v_mfma_f32_16x16x32_bf16 v[14:17], v[142:145], v[188:191], v[14:17]
	v_mfma_f32_16x16x32_bf16 v[6:9], v[150:153], v[188:191], v[6:9]
	s_setprio 0
	s_barrier
	s_add_u32 s36, s36, 0x80080
	s_addc_u32 s37, s37, 0
	s_add_i32 s66, s66, s28
	s_mov_b32 m0, s66
	s_nop 0
	global_load_lds_dwordx4 v0, s[36:37]
	s_add_i32 m0, s66, 0x2000
	s_add_u32 s24, s24, 0x80080
	s_addc_u32 s25, s25, 0
	global_load_lds_dwordx4 v134, s[36:37]
	s_mov_b32 m0, s49
	s_waitcnt vmcnt(6)
	s_barrier
	global_load_lds_dwordx4 v138, s[24:25]
	s_mov_b32 m0, s50
	s_nop 0
	global_load_lds_dwordx4 v136, s[24:25]
	s_setprio 1
	v_mfma_f32_16x16x32_bf16 v[58:61], v[192:195], v[160:163], v[58:61]
	v_mfma_f32_16x16x32_bf16 v[50:53], v[200:203], v[160:163], v[50:53]
	v_mfma_f32_16x16x32_bf16 v[42:45], v[192:195], v[168:171], v[42:45]
	v_mfma_f32_16x16x32_bf16 v[34:37], v[200:203], v[168:171], v[34:37]
	v_mfma_f32_16x16x32_bf16 v[26:29], v[192:195], v[176:179], v[26:29]
	v_mfma_f32_16x16x32_bf16 v[18:21], v[200:203], v[176:179], v[18:21]
	v_mfma_f32_16x16x32_bf16 v[10:13], v[192:195], v[184:187], v[10:13]
	v_mfma_f32_16x16x32_bf16 v[2:5], v[200:203], v[184:187], v[2:5]
	v_mfma_f32_16x16x32_bf16 v[58:61], v[196:199], v[164:167], v[58:61]
	v_mfma_f32_16x16x32_bf16 v[50:53], v[204:207], v[164:167], v[50:53]
	v_mfma_f32_16x16x32_bf16 v[42:45], v[196:199], v[172:175], v[42:45]
	v_mfma_f32_16x16x32_bf16 v[34:37], v[204:207], v[172:175], v[34:37]
	v_mfma_f32_16x16x32_bf16 v[26:29], v[196:199], v[180:183], v[26:29]
	v_mfma_f32_16x16x32_bf16 v[18:21], v[204:207], v[180:183], v[18:21]
	v_mfma_f32_16x16x32_bf16 v[10:13], v[196:199], v[188:191], v[10:13]
	v_mfma_f32_16x16x32_bf16 v[2:5], v[204:207], v[188:191], v[2:5]
	s_setprio 0
	s_add_i32 s65, s65, 2
	s_add_u32 s59, s59, 0x100
	s_addc_u32 s60, s60, 0
	s_add_u32 s61, s61, 0x100
	s_addc_u32 s64, s64, 0
	s_cmp_gt_u32 s65, 29
	s_barrier
